# attention window mask skipped on the three window tiles that lie fully inside the window; final RMSNorm hand-written like norm1/2; phase-0 adaLN second-round items moved to the weight-conversion workg
# speedup vs baseline: 1.0804x; 1.0029x over previous
.LBB0_16:
	v_readlane_b32 s23, v251, 0
	s_mov_b32 s100, s84
	s_cmp_lg_u32 s84, 0x100
	s_cbranch_scc1 .Lad_go
	s_movk_i32 s100, 0x3e8
	s_cmp_lt_u32 s23, 0x88
	s_cbranch_scc1 .Lad_go
	s_movk_i32 s100, 0x78
.Lad_go:
	s_branch .LBB0_19
.LBB0_17:
	s_or_b64 exec, exec, s[40:41]
.LBB0_18:
	s_mov_b32 s0, s100
	s_add_i32 s23, s0, s23

.LBB0_53:
	s_movk_i32 s100, 0x790
	s_mov_b32 s0, -1
	v_writelane_b32 v249, s0, 49
	s_mov_b32 s0, 0
	v_writelane_b32 v249, s0, 47
	s_barrier
	s_nop 0
	v_writelane_b32 v249, s1, 48
	s_andn2_b64 vcc, exec, s[24:25]
	s_cbranch_vccz .LBB0_14

.Lat_cons:
	v_mov_b32_e32 v10, v190
	v_mov_b32_e32 v11, v191
	v_lshlrev_b32_e32 v0, 2, v104
	s_barrier
	s_waitcnt vmcnt(0)
	v_mov_b32_e32 v2, v168
	v_mov_b32_e32 v3, v169
	v_mov_b32_e32 v4, v170
	v_mov_b32_e32 v5, v171
	v_mov_b32_e32 v6, v172
	v_mov_b32_e32 v7, v173
	v_mov_b32_e32 v8, v174
	v_mov_b32_e32 v9, v175
	v_cndmask_b32_e64 v12, 0, 1, s[48:49]
	v_cmp_ne_u32_e64 s[66:67], 1, v12
	s_mov_b32 s32, s74
	s_add_i32 s79, s30, -9
	s_andn2_b64 vcc, exec, s[48:49]
	s_cbranch_vccnz .LBB0_595
	v_add_u32_e32 v12, s74, v100
	v_ashrrev_i32_e32 v13, 6, v12
	v_and_b32_e32 v12, 63, v12
	v_cndmask_b32_e64 v12, v12, v13, s[36:37]
	v_lshl_or_b32 v12, v12, 4, v109
	v_ashrrev_i32_e32 v13, 31, v12
	v_lshl_add_u64 v[56:57], v[12:13], 3, s[64:65]
	v_mov_b32_e32 v107, v1
	global_load_dwordx4 v[12:15], v[56:57], off
	global_load_dwordx4 v[48:51], v[56:57], off offset:16
	global_load_dwordx4 v[52:55], v[56:57], off offset:32
	s_nop 0
	global_load_dwordx4 v[56:59], v[56:57], off offset:48
	v_lshl_add_u64 v[10:11], v[10:11], 0, v[106:107]
	global_load_dwordx4 v[60:63], v[10:11], off
	global_load_dwordx4 v[64:67], v[10:11], off offset:16
	s_waitcnt vmcnt(5)
	v_mov_b32_e32 v10, v13
	v_mov_b32_e32 v11, v15
	v_mov_b32_e32 v13, v14
	s_waitcnt vmcnt(4)
	v_mov_b32_e32 v14, v49
	v_mov_b32_e32 v15, v51
	v_mov_b32_e32 v49, v50
	s_waitcnt vmcnt(3)
	v_mov_b32_e32 v50, v53
	v_mov_b32_e32 v51, v55
	v_mov_b32_e32 v53, v54
	s_waitcnt vmcnt(2)
	v_mov_b32_e32 v54, v57
	v_mov_b32_e32 v55, v59
	s_waitcnt vmcnt(1)
	v_pk_mul_f32 v[10:11], v[60:61], v[10:11]
	v_pk_mul_f32 v[14:15], v[62:63], v[14:15]
	s_waitcnt vmcnt(0)
	v_pk_mul_f32 v[50:51], v[64:65], v[50:51]
	v_pk_mul_f32 v[54:55], v[66:67], v[54:55]
	v_mov_b32_e32 v57, v58
	v_cndmask_b32_e64 v11, v11, -v11, s[38:39]
	v_cndmask_b32_e64 v10, v10, -v10, s[38:39]
	v_cndmask_b32_e64 v15, v15, -v15, s[38:39]
	v_cndmask_b32_e64 v14, v14, -v14, s[38:39]
	v_cndmask_b32_e64 v51, v51, -v51, s[38:39]
	v_cndmask_b32_e64 v50, v50, -v50, s[38:39]
	v_cndmask_b32_e64 v55, v55, -v55, s[38:39]
	v_cndmask_b32_e64 v54, v54, -v54, s[38:39]
	v_pk_fma_f32 v[6:7], v[6:7], v[12:13], v[10:11]
	v_pk_fma_f32 v[8:9], v[8:9], v[48:49], v[14:15]
	v_pk_fma_f32 v[2:3], v[2:3], v[52:53], v[50:51]
	v_pk_fma_f32 v[4:5], v[4:5], v[56:57], v[54:55]

.Lat_go:
	ds_write_b16 v145, v0 offset:8192
	ds_write_b16 v145, v2 offset:8328
	ds_write_b16 v145, v3 offset:8464
	ds_write_b16 v145, v4 offset:8600
	ds_write_b16 v145, v5 offset:8736
	ds_write_b16 v145, v6 offset:8872
	ds_write_b16 v145, v7 offset:9008
	ds_write_b16 v145, v8 offset:9144
	s_and_b64 vcc, exec, s[66:67]
	s_waitcnt lgkmcnt(0)
	s_barrier
	ds_read_b128 v[2:5], v146
	ds_read_b128 v[6:9], v146 offset:4096
	ds_read_b128 v[10:13], v147
	ds_read_b128 v[152:155], v147 offset:4096
	ds_read_b128 v[156:159], v148
	s_waitcnt lgkmcnt(4)
	v_mfma_f32_32x32x16_bf16 v[64:79], v[2:5], v[80:83], 0
	ds_read_b128 v[2:5], v148 offset:4096
	s_waitcnt lgkmcnt(4)
	v_mfma_f32_32x32x16_bf16 v[48:63], v[6:9], v[80:83], 0
	ds_read_b128 v[6:9], v149
	s_waitcnt lgkmcnt(4)
	v_mfma_f32_32x32x16_bf16 v[64:79], v[10:13], v[84:87], v[64:79]
	ds_read_b128 v[10:13], v149 offset:4096
	s_waitcnt lgkmcnt(4)
	v_mfma_f32_32x32x16_bf16 v[48:63], v[152:155], v[84:87], v[48:63]
	s_waitcnt lgkmcnt(3)
	v_mfma_f32_32x32x16_bf16 v[64:79], v[156:159], v[88:91], v[64:79]
	s_waitcnt lgkmcnt(2)
	v_mfma_f32_32x32x16_bf16 v[48:63], v[2:5], v[88:91], v[48:63]
	s_waitcnt lgkmcnt(1)
	v_mfma_f32_32x32x16_bf16 v[64:79], v[6:9], v[92:95], v[64:79]
	s_waitcnt lgkmcnt(0)
	v_mfma_f32_32x32x16_bf16 v[48:63], v[10:13], v[92:95], v[48:63]
	s_cbranch_vccnz .LBB0_581
	s_cmp_lt_u32 s79, 3
	s_cbranch_scc1 .LBB0_581
	v_add_u32_e32 v0, s32, v101
	v_sub_u32_e32 v2, v108, v0
	v_cmp_lt_u32_e32 vcc, s72, v2
	v_sub_u32_e32 v2, v0, v108
	s_movk_i32 s0, 0x101
	s_nop 2
	v_cndmask_b32_e32 v64, v216, v64, vcc
	v_cmp_gt_u32_e32 vcc, s0, v2
	v_sub_u32_e32 v2, v110, v0
	s_nop 0
	v_cndmask_b32_e32 v65, v216, v65, vcc
	v_cmp_lt_u32_e32 vcc, s72, v2
	v_sub_u32_e32 v2, v111, v0
	s_nop 0
	v_cndmask_b32_e32 v66, v216, v66, vcc
	v_cmp_lt_u32_e32 vcc, s72, v2
	v_sub_u32_e32 v2, v112, v0
	s_nop 0
	v_cndmask_b32_e32 v67, v216, v67, vcc
	v_cmp_lt_u32_e32 vcc, s72, v2
	v_sub_u32_e32 v2, v113, v0
	s_nop 0
	v_cndmask_b32_e32 v68, v216, v68, vcc
	v_cmp_lt_u32_e32 vcc, s72, v2
	v_sub_u32_e32 v2, v114, v0
	s_nop 0
	v_cndmask_b32_e32 v69, v216, v69, vcc
	v_cmp_lt_u32_e32 vcc, s72, v2
	v_sub_u32_e32 v2, v115, v0
	s_nop 0
	v_cndmask_b32_e32 v70, v216, v70, vcc
	v_cmp_lt_u32_e32 vcc, s72, v2
	v_sub_u32_e32 v2, v116, v0
	s_nop 0
	v_cndmask_b32_e32 v71, v216, v71, vcc
	v_cmp_lt_u32_e32 vcc, s72, v2
	v_sub_u32_e32 v2, v117, v0
	s_nop 0
	v_cndmask_b32_e32 v72, v216, v72, vcc
	v_cmp_lt_u32_e32 vcc, s72, v2
	v_sub_u32_e32 v2, v118, v0
	s_nop 0
	v_cndmask_b32_e32 v73, v216, v73, vcc
	v_cmp_lt_u32_e32 vcc, s72, v2
	v_sub_u32_e32 v2, v119, v0
	s_nop 0
	v_cndmask_b32_e32 v74, v216, v74, vcc
	v_cmp_lt_u32_e32 vcc, s72, v2
	v_sub_u32_e32 v2, v120, v0
	s_nop 0
	v_cndmask_b32_e32 v75, v216, v75, vcc
	v_cmp_lt_u32_e32 vcc, s72, v2
	v_sub_u32_e32 v2, v121, v0
	s_nop 0
	v_cndmask_b32_e32 v76, v216, v76, vcc
	v_cmp_lt_u32_e32 vcc, s72, v2
	v_sub_u32_e32 v2, v122, v0
	s_nop 0
	v_cndmask_b32_e32 v77, v216, v77, vcc
	v_cmp_lt_u32_e32 vcc, s72, v2
	v_sub_u32_e32 v2, v123, v0
	s_nop 0
	v_cndmask_b32_e32 v78, v216, v78, vcc
	v_cmp_lt_u32_e32 vcc, s72, v2
	v_sub_u32_e32 v2, v124, v0
	s_nop 0
	v_cndmask_b32_e32 v79, v216, v79, vcc
	v_cmp_lt_u32_e32 vcc, s72, v2
	v_sub_u32_e32 v2, v125, v0
	s_nop 0
	v_cndmask_b32_e32 v48, v216, v48, vcc
	v_cmp_lt_u32_e32 vcc, s72, v2
	v_sub_u32_e32 v2, v126, v0
	s_nop 0
	v_cndmask_b32_e32 v49, v216, v49, vcc
	v_cmp_lt_u32_e32 vcc, s72, v2
	v_sub_u32_e32 v2, v127, v0
	s_nop 0
	v_cndmask_b32_e32 v50, v216, v50, vcc
	v_cmp_lt_u32_e32 vcc, s72, v2
	v_sub_u32_e32 v2, v128, v0
	s_nop 0
	v_cndmask_b32_e32 v51, v216, v51, vcc
	v_cmp_lt_u32_e32 vcc, s72, v2
	v_sub_u32_e32 v2, v129, v0
	s_nop 0
	v_cndmask_b32_e32 v52, v216, v52, vcc
	v_cmp_lt_u32_e32 vcc, s72, v2
	v_sub_u32_e32 v2, v130, v0
	s_nop 0
	v_cndmask_b32_e32 v53, v216, v53, vcc
	v_cmp_lt_u32_e32 vcc, s72, v2
	v_sub_u32_e32 v2, v131, v0
	s_nop 0
	v_cndmask_b32_e32 v54, v216, v54, vcc
	v_cmp_lt_u32_e32 vcc, s72, v2
	v_sub_u32_e32 v2, v132, v0
	s_nop 0
	v_cndmask_b32_e32 v55, v216, v55, vcc
	v_cmp_lt_u32_e32 vcc, s72, v2
	v_sub_u32_e32 v2, v133, v0
	s_nop 0
	v_cndmask_b32_e32 v56, v216, v56, vcc
	v_cmp_lt_u32_e32 vcc, s72, v2
	v_sub_u32_e32 v2, v138, v0
	s_nop 0
	v_cndmask_b32_e32 v57, v216, v57, vcc
	v_cmp_lt_u32_e32 vcc, s72, v2
	v_sub_u32_e32 v2, v139, v0
	s_nop 0
	v_cndmask_b32_e32 v58, v216, v58, vcc
	v_cmp_lt_u32_e32 vcc, s72, v2
	v_sub_u32_e32 v2, v140, v0
	s_nop 0
	v_cndmask_b32_e32 v59, v216, v59, vcc
	v_cmp_lt_u32_e32 vcc, s72, v2
	v_sub_u32_e32 v2, v141, v0
	s_nop 0
	v_cndmask_b32_e32 v60, v216, v60, vcc
	v_cmp_lt_u32_e32 vcc, s72, v2
	v_sub_u32_e32 v2, v142, v0
	v_sub_u32_e32 v0, v143, v0
	v_cndmask_b32_e32 v61, v216, v61, vcc
	v_cmp_lt_u32_e32 vcc, s72, v2
	s_nop 1
	v_cndmask_b32_e32 v62, v216, v62, vcc
	v_cmp_lt_u32_e32 vcc, s72, v0
	s_nop 1
	v_cndmask_b32_e32 v63, v216, v63, vcc
	s_branch .LBB0_581

.LBB0_1878:
	s_cmp_lg_u32 s84, 0x100
	s_cbranch_scc1 .Lfn_orig
	v_readlane_b32 s20, v251, 0
	v_readfirstlane_b32 s21, v135
	v_readlane_b32 s8, v251, 61
	v_readlane_b32 s9, v251, 62
	s_lshr_b32 s21, s21, 6
	s_lshl_b32 s20, s20, 3
	s_add_i32 s20, s20, s21
	v_mbcnt_lo_u32_b32 v0, -1, 0
	v_mbcnt_hi_u32_b32 v0, -1, v0
	v_lshlrev_b32_e32 v12, 4, v0
	v_xor_b32_e32 v6, 32, v0
	v_lshlrev_b32_e32 v6, 2, v6
	v_xor_b32_e32 v7, 16, v0
	v_lshlrev_b32_e32 v7, 2, v7
	v_mov_b32_e32 v18, 0x358637bd
	s_lshl_b32 s14, s20, 12
	s_add_u32 s18, s8, s14
	s_addc_u32 s19, s9, 0
	s_add_u32 s44, s92, s14
	s_addc_u32 s45, s93, 0
	global_load_dwordx4 v[30:33], v12, s[18:19]
	global_load_dwordx4 v[34:37], v12, s[18:19] offset:1024
	global_load_dwordx4 v[38:41], v12, s[18:19] offset:2048
	global_load_dwordx4 v[42:45], v12, s[18:19] offset:3072
	s_add_u32 s18, s18, 0x800000
	s_addc_u32 s19, s19, 0
	global_load_dwordx4 v[46:49], v12, s[18:19]
	global_load_dwordx4 v[50:53], v12, s[18:19] offset:1024
	global_load_dwordx4 v[54:57], v12, s[18:19] offset:2048
	global_load_dwordx4 v[58:61], v12, s[18:19] offset:3072
	s_add_u32 s18, s18, 0x800000
	s_addc_u32 s19, s19, 0
	global_load_dwordx4 v[62:65], v12, s[18:19]
	global_load_dwordx4 v[66:69], v12, s[18:19] offset:1024
	global_load_dwordx4 v[70:73], v12, s[18:19] offset:2048
	global_load_dwordx4 v[74:77], v12, s[18:19] offset:3072
	s_add_u32 s18, s18, 0x800000
	s_addc_u32 s19, s19, 0
	global_load_dwordx4 v[78:81], v12, s[90:91]
	global_load_dwordx4 v[82:85], v12, s[90:91] offset:1024
	global_load_dwordx4 v[86:89], v12, s[90:91] offset:2048
	global_load_dwordx4 v[90:93], v12, s[90:91] offset:3072
	s_waitcnt vmcnt(12)
	v_pk_mul_f32 v[24:25], v[30:31], v[30:31]
	v_pk_mul_f32 v[26:27], v[32:33], v[32:33]
	v_pk_fma_f32 v[24:25], v[34:35], v[34:35], v[24:25]
	v_pk_fma_f32 v[26:27], v[36:37], v[36:37], v[26:27]
	v_pk_fma_f32 v[24:25], v[38:39], v[38:39], v[24:25]
	v_pk_fma_f32 v[26:27], v[40:41], v[40:41], v[26:27]
	v_pk_fma_f32 v[24:25], v[42:43], v[42:43], v[24:25]
	v_pk_fma_f32 v[26:27], v[44:45], v[44:45], v[26:27]
	v_pk_add_f32 v[24:25], v[24:25], v[26:27]
	s_nop 0
	v_add_f32_e32 v19, v24, v25
	s_nop 1
	v_add_f32_dpp v19, v19, v19 quad_perm:[1,0,3,2] row_mask:0xf bank_mask:0xf
	s_nop 1
	v_add_f32_dpp v19, v19, v19 quad_perm:[2,3,0,1] row_mask:0xf bank_mask:0xf
	s_nop 1
	v_add_f32_dpp v19, v19, v19 row_half_mirror row_mask:0xf bank_mask:0xf
	s_nop 1
	v_add_f32_dpp v19, v19, v19 row_mirror row_mask:0xf bank_mask:0xf
	ds_bpermute_b32 v20, v7, v19
	s_waitcnt lgkmcnt(0)
	v_add_f32_e32 v19, v19, v20
	ds_bpermute_b32 v20, v6, v19
	s_waitcnt lgkmcnt(0)
	v_add_f32_e32 v19, v19, v20
	v_fmamk_f32 v19, v19, 0x3a800000, v18
	v_rsq_f32_e32 v22, v19
	s_waitcnt vmcnt(0)
	s_nop 0
	v_pk_mul_f32 v[30:31], v[30:31], v[22:23] op_sel_hi:[1,0]
	v_pk_mul_f32 v[32:33], v[32:33], v[22:23] op_sel_hi:[1,0]
	v_pk_mul_f32 v[30:31], v[30:31], v[78:79]
	v_pk_mul_f32 v[32:33], v[32:33], v[80:81]
	global_store_dwordx4 v12, v[30:33], s[44:45]
	v_pk_mul_f32 v[34:35], v[34:35], v[22:23] op_sel_hi:[1,0]
	v_pk_mul_f32 v[36:37], v[36:37], v[22:23] op_sel_hi:[1,0]
	v_pk_mul_f32 v[34:35], v[34:35], v[82:83]
	v_pk_mul_f32 v[36:37], v[36:37], v[84:85]
	global_store_dwordx4 v12, v[34:37], s[44:45] offset:1024
	v_pk_mul_f32 v[38:39], v[38:39], v[22:23] op_sel_hi:[1,0]
	v_pk_mul_f32 v[40:41], v[40:41], v[22:23] op_sel_hi:[1,0]
	v_pk_mul_f32 v[38:39], v[38:39], v[86:87]
	v_pk_mul_f32 v[40:41], v[40:41], v[88:89]
	global_store_dwordx4 v12, v[38:41], s[44:45] offset:2048
	v_pk_mul_f32 v[42:43], v[42:43], v[22:23] op_sel_hi:[1,0]
	v_pk_mul_f32 v[44:45], v[44:45], v[22:23] op_sel_hi:[1,0]
	v_pk_mul_f32 v[42:43], v[42:43], v[90:91]
	v_pk_mul_f32 v[44:45], v[44:45], v[92:93]
	global_store_dwordx4 v12, v[42:45], s[44:45] offset:3072
	s_add_u32 s44, s44, 0x800000
	s_addc_u32 s45, s45, 0
	global_load_dwordx4 v[30:33], v12, s[18:19]
	global_load_dwordx4 v[34:37], v12, s[18:19] offset:1024
	global_load_dwordx4 v[38:41], v12, s[18:19] offset:2048
	global_load_dwordx4 v[42:45], v12, s[18:19] offset:3072
	s_add_u32 s18, s18, 0x800000
	s_addc_u32 s19, s19, 0
	s_waitcnt vmcnt(16)
	v_pk_mul_f32 v[24:25], v[46:47], v[46:47]
	v_pk_mul_f32 v[26:27], v[48:49], v[48:49]
	v_pk_fma_f32 v[24:25], v[50:51], v[50:51], v[24:25]
	v_pk_fma_f32 v[26:27], v[52:53], v[52:53], v[26:27]
	v_pk_fma_f32 v[24:25], v[54:55], v[54:55], v[24:25]
	v_pk_fma_f32 v[26:27], v[56:57], v[56:57], v[26:27]
	v_pk_fma_f32 v[24:25], v[58:59], v[58:59], v[24:25]
	v_pk_fma_f32 v[26:27], v[60:61], v[60:61], v[26:27]
	v_pk_add_f32 v[24:25], v[24:25], v[26:27]
	s_nop 0
	v_add_f32_e32 v19, v24, v25
	s_nop 1
	v_add_f32_dpp v19, v19, v19 quad_perm:[1,0,3,2] row_mask:0xf bank_mask:0xf
	s_nop 1
	v_add_f32_dpp v19, v19, v19 quad_perm:[2,3,0,1] row_mask:0xf bank_mask:0xf
	s_nop 1
	v_add_f32_dpp v19, v19, v19 row_half_mirror row_mask:0xf bank_mask:0xf
	s_nop 1
	v_add_f32_dpp v19, v19, v19 row_mirror row_mask:0xf bank_mask:0xf
	ds_bpermute_b32 v20, v7, v19
	s_waitcnt lgkmcnt(0)
	v_add_f32_e32 v19, v19, v20
	ds_bpermute_b32 v20, v6, v19
	s_waitcnt lgkmcnt(0)
	v_add_f32_e32 v19, v19, v20
	v_fmamk_f32 v19, v19, 0x3a800000, v18
	v_rsq_f32_e32 v22, v19
	s_nop 0
	v_pk_mul_f32 v[46:47], v[46:47], v[22:23] op_sel_hi:[1,0]
	v_pk_mul_f32 v[48:49], v[48:49], v[22:23] op_sel_hi:[1,0]
	v_pk_mul_f32 v[46:47], v[46:47], v[78:79]
	v_pk_mul_f32 v[48:49], v[48:49], v[80:81]
	global_store_dwordx4 v12, v[46:49], s[44:45]
	v_pk_mul_f32 v[50:51], v[50:51], v[22:23] op_sel_hi:[1,0]
	v_pk_mul_f32 v[52:53], v[52:53], v[22:23] op_sel_hi:[1,0]
	v_pk_mul_f32 v[50:51], v[50:51], v[82:83]
	v_pk_mul_f32 v[52:53], v[52:53], v[84:85]
	global_store_dwordx4 v12, v[50:53], s[44:45] offset:1024
	v_pk_mul_f32 v[54:55], v[54:55], v[22:23] op_sel_hi:[1,0]
	v_pk_mul_f32 v[56:57], v[56:57], v[22:23] op_sel_hi:[1,0]
	v_pk_mul_f32 v[54:55], v[54:55], v[86:87]
	v_pk_mul_f32 v[56:57], v[56:57], v[88:89]
	global_store_dwordx4 v12, v[54:57], s[44:45] offset:2048
	v_pk_mul_f32 v[58:59], v[58:59], v[22:23] op_sel_hi:[1,0]
	v_pk_mul_f32 v[60:61], v[60:61], v[22:23] op_sel_hi:[1,0]
	v_pk_mul_f32 v[58:59], v[58:59], v[90:91]
	v_pk_mul_f32 v[60:61], v[60:61], v[92:93]
	global_store_dwordx4 v12, v[58:61], s[44:45] offset:3072
	s_add_u32 s44, s44, 0x800000
	s_addc_u32 s45, s45, 0
	global_load_dwordx4 v[46:49], v12, s[18:19]
	global_load_dwordx4 v[50:53], v12, s[18:19] offset:1024
	global_load_dwordx4 v[54:57], v12, s[18:19] offset:2048
	global_load_dwordx4 v[58:61], v12, s[18:19] offset:3072
	s_add_u32 s18, s18, 0x800000
	s_addc_u32 s19, s19, 0
	s_waitcnt vmcnt(20)
	v_pk_mul_f32 v[24:25], v[62:63], v[62:63]
	v_pk_mul_f32 v[26:27], v[64:65], v[64:65]
	v_pk_fma_f32 v[24:25], v[66:67], v[66:67], v[24:25]
	v_pk_fma_f32 v[26:27], v[68:69], v[68:69], v[26:27]
	v_pk_fma_f32 v[24:25], v[70:71], v[70:71], v[24:25]
	v_pk_fma_f32 v[26:27], v[72:73], v[72:73], v[26:27]
	v_pk_fma_f32 v[24:25], v[74:75], v[74:75], v[24:25]
	v_pk_fma_f32 v[26:27], v[76:77], v[76:77], v[26:27]
	v_pk_add_f32 v[24:25], v[24:25], v[26:27]
	s_nop 0
	v_add_f32_e32 v19, v24, v25
	s_nop 1
	v_add_f32_dpp v19, v19, v19 quad_perm:[1,0,3,2] row_mask:0xf bank_mask:0xf
	s_nop 1
	v_add_f32_dpp v19, v19, v19 quad_perm:[2,3,0,1] row_mask:0xf bank_mask:0xf
	s_nop 1
	v_add_f32_dpp v19, v19, v19 row_half_mirror row_mask:0xf bank_mask:0xf
	s_nop 1
	v_add_f32_dpp v19, v19, v19 row_mirror row_mask:0xf bank_mask:0xf
	ds_bpermute_b32 v20, v7, v19
	s_waitcnt lgkmcnt(0)
	v_add_f32_e32 v19, v19, v20
	ds_bpermute_b32 v20, v6, v19
	s_waitcnt lgkmcnt(0)
	v_add_f32_e32 v19, v19, v20
	v_fmamk_f32 v19, v19, 0x3a800000, v18
	v_rsq_f32_e32 v22, v19
	s_nop 0
	v_pk_mul_f32 v[62:63], v[62:63], v[22:23] op_sel_hi:[1,0]
	v_pk_mul_f32 v[64:65], v[64:65], v[22:23] op_sel_hi:[1,0]
	v_pk_mul_f32 v[62:63], v[62:63], v[78:79]
	v_pk_mul_f32 v[64:65], v[64:65], v[80:81]
	global_store_dwordx4 v12, v[62:65], s[44:45]
	v_pk_mul_f32 v[66:67], v[66:67], v[22:23] op_sel_hi:[1,0]
	v_pk_mul_f32 v[68:69], v[68:69], v[22:23] op_sel_hi:[1,0]
	v_pk_mul_f32 v[66:67], v[66:67], v[82:83]
	v_pk_mul_f32 v[68:69], v[68:69], v[84:85]
	global_store_dwordx4 v12, v[66:69], s[44:45] offset:1024
	v_pk_mul_f32 v[70:71], v[70:71], v[22:23] op_sel_hi:[1,0]
	v_pk_mul_f32 v[72:73], v[72:73], v[22:23] op_sel_hi:[1,0]
	v_pk_mul_f32 v[70:71], v[70:71], v[86:87]
	v_pk_mul_f32 v[72:73], v[72:73], v[88:89]
	global_store_dwordx4 v12, v[70:73], s[44:45] offset:2048
	v_pk_mul_f32 v[74:75], v[74:75], v[22:23] op_sel_hi:[1,0]
	v_pk_mul_f32 v[76:77], v[76:77], v[22:23] op_sel_hi:[1,0]
	v_pk_mul_f32 v[74:75], v[74:75], v[90:91]
	v_pk_mul_f32 v[76:77], v[76:77], v[92:93]
	global_store_dwordx4 v12, v[74:77], s[44:45] offset:3072
	s_add_u32 s44, s44, 0x800000
	s_addc_u32 s45, s45, 0
	global_load_dwordx4 v[62:65], v12, s[18:19]
	global_load_dwordx4 v[66:69], v12, s[18:19] offset:1024
	global_load_dwordx4 v[70:73], v12, s[18:19] offset:2048
	global_load_dwordx4 v[74:77], v12, s[18:19] offset:3072
	s_add_u32 s18, s18, 0x800000
	s_addc_u32 s19, s19, 0
	s_waitcnt vmcnt(16)
	v_pk_mul_f32 v[24:25], v[30:31], v[30:31]
	v_pk_mul_f32 v[26:27], v[32:33], v[32:33]
	v_pk_fma_f32 v[24:25], v[34:35], v[34:35], v[24:25]
	v_pk_fma_f32 v[26:27], v[36:37], v[36:37], v[26:27]
	v_pk_fma_f32 v[24:25], v[38:39], v[38:39], v[24:25]
	v_pk_fma_f32 v[26:27], v[40:41], v[40:41], v[26:27]
	v_pk_fma_f32 v[24:25], v[42:43], v[42:43], v[24:25]
	v_pk_fma_f32 v[26:27], v[44:45], v[44:45], v[26:27]
	v_pk_add_f32 v[24:25], v[24:25], v[26:27]
	s_nop 0
	v_add_f32_e32 v19, v24, v25
	s_nop 1
	v_add_f32_dpp v19, v19, v19 quad_perm:[1,0,3,2] row_mask:0xf bank_mask:0xf
	s_nop 1
	v_add_f32_dpp v19, v19, v19 quad_perm:[2,3,0,1] row_mask:0xf bank_mask:0xf
	s_nop 1
	v_add_f32_dpp v19, v19, v19 row_half_mirror row_mask:0xf bank_mask:0xf
	s_nop 1
	v_add_f32_dpp v19, v19, v19 row_mirror row_mask:0xf bank_mask:0xf
	ds_bpermute_b32 v20, v7, v19
	s_waitcnt lgkmcnt(0)
	v_add_f32_e32 v19, v19, v20
	ds_bpermute_b32 v20, v6, v19
	s_waitcnt lgkmcnt(0)
	v_add_f32_e32 v19, v19, v20
	v_fmamk_f32 v19, v19, 0x3a800000, v18
	v_rsq_f32_e32 v22, v19
	s_nop 0
	v_pk_mul_f32 v[30:31], v[30:31], v[22:23] op_sel_hi:[1,0]
	v_pk_mul_f32 v[32:33], v[32:33], v[22:23] op_sel_hi:[1,0]
	v_pk_mul_f32 v[30:31], v[30:31], v[78:79]
	v_pk_mul_f32 v[32:33], v[32:33], v[80:81]
	global_store_dwordx4 v12, v[30:33], s[44:45]
	v_pk_mul_f32 v[34:35], v[34:35], v[22:23] op_sel_hi:[1,0]
	v_pk_mul_f32 v[36:37], v[36:37], v[22:23] op_sel_hi:[1,0]
	v_pk_mul_f32 v[34:35], v[34:35], v[82:83]
	v_pk_mul_f32 v[36:37], v[36:37], v[84:85]
	global_store_dwordx4 v12, v[34:37], s[44:45] offset:1024
	v_pk_mul_f32 v[38:39], v[38:39], v[22:23] op_sel_hi:[1,0]
	v_pk_mul_f32 v[40:41], v[40:41], v[22:23] op_sel_hi:[1,0]
	v_pk_mul_f32 v[38:39], v[38:39], v[86:87]
	v_pk_mul_f32 v[40:41], v[40:41], v[88:89]
	global_store_dwordx4 v12, v[38:41], s[44:45] offset:2048
	v_pk_mul_f32 v[42:43], v[42:43], v[22:23] op_sel_hi:[1,0]
	v_pk_mul_f32 v[44:45], v[44:45], v[22:23] op_sel_hi:[1,0]
	v_pk_mul_f32 v[42:43], v[42:43], v[90:91]
	v_pk_mul_f32 v[44:45], v[44:45], v[92:93]
	global_store_dwordx4 v12, v[42:45], s[44:45] offset:3072
	s_add_u32 s44, s44, 0x800000
	s_addc_u32 s45, s45, 0
	s_waitcnt vmcnt(12)
	v_pk_mul_f32 v[24:25], v[46:47], v[46:47]
	v_pk_mul_f32 v[26:27], v[48:49], v[48:49]
	v_pk_fma_f32 v[24:25], v[50:51], v[50:51], v[24:25]
	v_pk_fma_f32 v[26:27], v[52:53], v[52:53], v[26:27]
	v_pk_fma_f32 v[24:25], v[54:55], v[54:55], v[24:25]
	v_pk_fma_f32 v[26:27], v[56:57], v[56:57], v[26:27]
	v_pk_fma_f32 v[24:25], v[58:59], v[58:59], v[24:25]
	v_pk_fma_f32 v[26:27], v[60:61], v[60:61], v[26:27]
	v_pk_add_f32 v[24:25], v[24:25], v[26:27]
	s_nop 0
	v_add_f32_e32 v19, v24, v25
	s_nop 1
	v_add_f32_dpp v19, v19, v19 quad_perm:[1,0,3,2] row_mask:0xf bank_mask:0xf
	s_nop 1
	v_add_f32_dpp v19, v19, v19 quad_perm:[2,3,0,1] row_mask:0xf bank_mask:0xf
	s_nop 1
	v_add_f32_dpp v19, v19, v19 row_half_mirror row_mask:0xf bank_mask:0xf
	s_nop 1
	v_add_f32_dpp v19, v19, v19 row_mirror row_mask:0xf bank_mask:0xf
	ds_bpermute_b32 v20, v7, v19
	s_waitcnt lgkmcnt(0)
	v_add_f32_e32 v19, v19, v20
	ds_bpermute_b32 v20, v6, v19
	s_waitcnt lgkmcnt(0)
	v_add_f32_e32 v19, v19, v20
	v_fmamk_f32 v19, v19, 0x3a800000, v18
	v_rsq_f32_e32 v22, v19
	s_nop 0
	v_pk_mul_f32 v[46:47], v[46:47], v[22:23] op_sel_hi:[1,0]
	v_pk_mul_f32 v[48:49], v[48:49], v[22:23] op_sel_hi:[1,0]
	v_pk_mul_f32 v[46:47], v[46:47], v[78:79]
	v_pk_mul_f32 v[48:49], v[48:49], v[80:81]
	global_store_dwordx4 v12, v[46:49], s[44:45]
	v_pk_mul_f32 v[50:51], v[50:51], v[22:23] op_sel_hi:[1,0]
	v_pk_mul_f32 v[52:53], v[52:53], v[22:23] op_sel_hi:[1,0]
	v_pk_mul_f32 v[50:51], v[50:51], v[82:83]
	v_pk_mul_f32 v[52:53], v[52:53], v[84:85]
	global_store_dwordx4 v12, v[50:53], s[44:45] offset:1024
	v_pk_mul_f32 v[54:55], v[54:55], v[22:23] op_sel_hi:[1,0]
	v_pk_mul_f32 v[56:57], v[56:57], v[22:23] op_sel_hi:[1,0]
	v_pk_mul_f32 v[54:55], v[54:55], v[86:87]
	v_pk_mul_f32 v[56:57], v[56:57], v[88:89]
	global_store_dwordx4 v12, v[54:57], s[44:45] offset:2048
	v_pk_mul_f32 v[58:59], v[58:59], v[22:23] op_sel_hi:[1,0]
	v_pk_mul_f32 v[60:61], v[60:61], v[22:23] op_sel_hi:[1,0]
	v_pk_mul_f32 v[58:59], v[58:59], v[90:91]
	v_pk_mul_f32 v[60:61], v[60:61], v[92:93]
	global_store_dwordx4 v12, v[58:61], s[44:45] offset:3072
	s_add_u32 s44, s44, 0x800000
	s_addc_u32 s45, s45, 0
	s_waitcnt vmcnt(8)
	v_pk_mul_f32 v[24:25], v[62:63], v[62:63]
	v_pk_mul_f32 v[26:27], v[64:65], v[64:65]
	v_pk_fma_f32 v[24:25], v[66:67], v[66:67], v[24:25]
	v_pk_fma_f32 v[26:27], v[68:69], v[68:69], v[26:27]
	v_pk_fma_f32 v[24:25], v[70:71], v[70:71], v[24:25]
	v_pk_fma_f32 v[26:27], v[72:73], v[72:73], v[26:27]
	v_pk_fma_f32 v[24:25], v[74:75], v[74:75], v[24:25]
	v_pk_fma_f32 v[26:27], v[76:77], v[76:77], v[26:27]
	v_pk_add_f32 v[24:25], v[24:25], v[26:27]
	s_nop 0
	v_add_f32_e32 v19, v24, v25
	s_nop 1
	v_add_f32_dpp v19, v19, v19 quad_perm:[1,0,3,2] row_mask:0xf bank_mask:0xf
	s_nop 1
	v_add_f32_dpp v19, v19, v19 quad_perm:[2,3,0,1] row_mask:0xf bank_mask:0xf
	s_nop 1
	v_add_f32_dpp v19, v19, v19 row_half_mirror row_mask:0xf bank_mask:0xf
	s_nop 1
	v_add_f32_dpp v19, v19, v19 row_mirror row_mask:0xf bank_mask:0xf
	ds_bpermute_b32 v20, v7, v19
	s_waitcnt lgkmcnt(0)
	v_add_f32_e32 v19, v19, v20
	ds_bpermute_b32 v20, v6, v19
	s_waitcnt lgkmcnt(0)
	v_add_f32_e32 v19, v19, v20
	v_fmamk_f32 v19, v19, 0x3a800000, v18
	v_rsq_f32_e32 v22, v19
	s_nop 0
	v_pk_mul_f32 v[62:63], v[62:63], v[22:23] op_sel_hi:[1,0]
	v_pk_mul_f32 v[64:65], v[64:65], v[22:23] op_sel_hi:[1,0]
	v_pk_mul_f32 v[62:63], v[62:63], v[78:79]
	v_pk_mul_f32 v[64:65], v[64:65], v[80:81]
	global_store_dwordx4 v12, v[62:65], s[44:45]
	v_pk_mul_f32 v[66:67], v[66:67], v[22:23] op_sel_hi:[1,0]
	v_pk_mul_f32 v[68:69], v[68:69], v[22:23] op_sel_hi:[1,0]
	v_pk_mul_f32 v[66:67], v[66:67], v[82:83]
	v_pk_mul_f32 v[68:69], v[68:69], v[84:85]
	global_store_dwordx4 v12, v[66:69], s[44:45] offset:1024
	v_pk_mul_f32 v[70:71], v[70:71], v[22:23] op_sel_hi:[1,0]
	v_pk_mul_f32 v[72:73], v[72:73], v[22:23] op_sel_hi:[1,0]
	v_pk_mul_f32 v[70:71], v[70:71], v[86:87]
	v_pk_mul_f32 v[72:73], v[72:73], v[88:89]
	global_store_dwordx4 v12, v[70:73], s[44:45] offset:2048
	v_pk_mul_f32 v[74:75], v[74:75], v[22:23] op_sel_hi:[1,0]
	v_pk_mul_f32 v[76:77], v[76:77], v[22:23] op_sel_hi:[1,0]
	v_pk_mul_f32 v[74:75], v[74:75], v[90:91]
	v_pk_mul_f32 v[76:77], v[76:77], v[92:93]
	global_store_dwordx4 v12, v[74:77], s[44:45] offset:3072
	s_add_u32 s44, s44, 0x800000
	s_addc_u32 s45, s45, 0
	s_branch .LBB0_1879
